# A/B: same as previous but with no s_setprio at all
# baseline (speedup 1.0000x reference)
.LBB0_24:
	v_readlane_b32 s48, v253, 16
	s_mov_b64 s[82:83], 0x60000
	s_movk_i32 s90, 0x104
	v_readfirstlane_b32 s2, v193
	s_nop 1
	s_cmpk_gt_u32 s2, 0xff
	s_cbranch_scc1 .Lprio_skip
.Lprio_skip:
	s_mov_b64 s[28:29], -1
	s_mov_b64 s[0:1], 0
	s_cmp_lt_i32 s84, 1
	s_mov_b64 s[22:23], 0
	v_readlane_b32 s49, v253, 17
	v_readlane_b32 s50, v253, 18
	v_readlane_b32 s51, v253, 19
	v_readlane_b32 s52, v253, 20
	v_readlane_b32 s53, v253, 21
	v_readlane_b32 s54, v253, 22
	v_readlane_b32 s55, v253, 23
	v_readlane_b32 s56, v253, 24
	v_readlane_b32 s57, v253, 25
	v_readlane_b32 s58, v253, 26
	v_readlane_b32 s59, v253, 27
	v_readlane_b32 s60, v253, 28
	v_readlane_b32 s61, v253, 29
	v_readlane_b32 s62, v253, 30
	v_readlane_b32 s63, v253, 31
	s_cbranch_scc0 .LBB0_27
	s_and_b64 vcc, exec, s[28:29]
	s_cbranch_vccnz .LBB0_37
